# odd workgroups run the two independent parts of the hproj+merge and H3+gates phases in the opposite order (memory-bound and MFMA parts overlap across workgroups)
# baseline (speedup 1.0000x reference)
; #define REP(n) for (int rep_ = 0; rep_ < 1 + (n); ++rep_)
;     __host__ __device__ bool next(int i, Unit& u) const {
;         const long L = (long)i * G + c; if (L >= nwg) return false;
;         int wgid = (int)L; { const int q = nwg / NXCD, r = nwg % NXCD, xcd = wgid % NXCD, off = wgid / NXCD; wgid = (xcd < r ? xcd * (q + 1) : r * (q + 1) + (xcd - r) * q) + off; }
; __global__ void __launch_bounds__(512, 2) fwd_megakernel(Args a) {
;     ...
;         REP(PROBE_GEMM) { FRESH(); run_gemm(L, Xb, D, (const bf16*)(ws + W_IN) + (size_t)NATT * D, D, M, NH2, D, G, bid, EpiZ{Z, NH2, ssq}); }
;         { FRESH(); merge_phase((const bf16*)(ws + WS_OG), (const float*)(ws + WS_LSE), (bf16*)(ws + WS_AO), gtid, NGT); }
.LBB0_440:
	v_readlane_b32 s100, v252, 0
	s_nop 3
	s_bfe_u32 s100, s100, 0x10003
	v_writelane_b32 v255, s100, 62
.Lswap5_first:
	s_or_b64 exec, exec, s[0:1]
	s_mov_b64 s[0:1], 0
	v_mov_b32_e32 v0, v238
	s_mov_b32 s22, s29
	v_readlane_b32 s23, v252, 0
	s_waitcnt vmcnt(12)
	v_mov_b32_e32 v16, v238
	s_waitcnt lgkmcnt(0)
	s_barrier
	s_cmpk_lt_i32 s23, 0x400
	v_readfirstlane_b32 s4, v16
	s_cbranch_scc0 .LBB0_464
	v_readlane_b32 s100, v255, 62
	s_nop 3
	s_cmp_eq_u32 s100, 1
	s_cbranch_scc0 .Lswap5_g
	s_mov_b32 s24, 0x100000
	s_branch .LBB0_464
.Lswap5_g:
	s_ashr_i32 s24, s23, 31
	s_lshr_b32 s2, s24, 29
	s_add_i32 s6, s23, s2
	s_and_b32 s2, s6, -8
	s_sub_i32 s5, s23, s2
	s_cmp_gt_i32 s5, -1
	s_mov_b64 s[2:3], -1
	s_cbranch_scc0 .LBB0_443
	s_lshl_b32 s9, s5, 7
	s_mov_b64 s[2:3], 0

; DI void merge_phase(const bf16* OG, const float* LSE, bf16* AO, int gtid, int NGT) {
;     for (int idx0 = gtid; idx0 < M * 64; idx0 += 4 * NGT) {
;         u32x4 xa[4], xb[4], xd[4]; float l0[4], l1[4], l2[4]; bf16* op[4];
; #pragma unroll
;         for (int u = 0; u < 4; ++u) { const int idx = idx0 + u * NGT; const bool ok = idx < M * 64; const int tok = ok ? idx >> 6 : 0, h = (idx >> 4) & 3, c = idx & 15;
;             l0[u] = LSE[(size_t)tok * 12 + h]; l1[u] = LSE[(size_t)tok * 12 + 4 + h]; l2[u] = LSE[(size_t)tok * 12 + 8 + h];
;             const bf16* p = OG + (size_t)tok * 1536 + h * 128 + 8 * c; xa[u] = *(const u32x4*)p; xb[u] = *(const u32x4*)(p + 512); xd[u] = *(const u32x4*)(p + 1024);
;             op[u] = ok ? AO + (size_t)tok * 512 + h * 128 + 8 * c : nullptr; }
.LBB0_464:
	v_readlane_b32 s100, v255, 62
	s_nop 3
	s_cmp_eq_u32 s100, 2
	s_cbranch_scc1 .Lswap5_b5
	s_mov_b64 s[0:1], 0
	v_mov_b32_e32 v0, v238
	s_mov_b32 s10, s29
	v_readlane_b32 s11, v252, 0
	s_nop 1
	v_lshl_add_u32 v40, s11, 9, v0
	v_cmp_gt_i32_e32 vcc, s24, v40
	s_and_saveexec_b64 s[2:3], vcc
	s_xor_b64 s[2:3], exec, s[2:3]
	s_cbranch_execz .LBB0_474
	s_add_u32 s0, s78, s0
	s_addc_u32 s1, s79, s1
	s_lshl_b32 s14, s10, 9
	s_add_u32 s4, s0, 0xf400000
	s_addc_u32 s5, s1, 0
	s_add_u32 s6, s0, 0x14600000
	s_addc_u32 s7, s1, 0
	s_add_u32 s8, s0, 0x12400000
	v_lshlrev_b32_e32 v0, 3, v0
	s_addc_u32 s9, s1, 0
	s_waitcnt vmcnt(9)
	v_lshl_add_u32 v61, s11, 12, v0
	s_lshl_b32 s15, s10, 14
	s_lshl_b32 s16, s10, 10
	s_mul_i32 s17, s10, 0x600
	s_mov_b64 s[10:11], 0
	s_branch .LBB0_467

; __device__ __forceinline__ unsigned xb_add(unsigned* p, unsigned v) { return __hip_atomic_fetch_add(p, v, __ATOMIC_RELAXED, __HIP_MEMORY_SCOPE_AGENT); }
; __device__ __forceinline__ void xcd_barrier(const XcdBarrier& b) {
;     asm volatile("s_waitcnt vmcnt(0)" ::: "memory");
;     __syncthreads();
;     if (threadIdx.x == 0) {
;         unsigned* bar = b.bar;
;         __builtin_amdgcn_s_waitcnt(0);
;         unsigned nloc = b.st[0], nx = b.st[1];
;         if (nloc == 0u) { xcd_barrier_complete(bar, b.x, nloc, nx); b.st[0] = nloc; b.st[1] = nx; }
;         const unsigned old = xb_add(&bar[XB_XSUB(b.x)], 1u);
.LBB0_474:
	s_or_b64 exec, exec, s[2:3]
	v_readlane_b32 s100, v255, 62
	s_nop 3
	s_cmp_eq_u32 s100, 1
	s_cbranch_scc0 .Lswap5_b5
	s_mov_b32 s100, 2
	v_writelane_b32 v255, s100, 62
	s_branch .Lswap5_first
.Lswap5_b5:
	s_waitcnt vmcnt(0)
	s_barrier
	s_and_saveexec_b64 s[0:1], s[80:81]
	s_cbranch_execz .LBB0_522
	v_readlane_b32 s2, v254, 25
	s_waitcnt vmcnt(0) expcnt(0) lgkmcnt(0)
	s_nop 0
	v_mov_b32_e32 v0, s2
	ds_read_b32 v3, v0
	v_readlane_b32 s2, v254, 26
	s_waitcnt lgkmcnt(0)
	v_cmp_ne_u32_e32 vcc, 0, v3
	v_mov_b32_e32 v0, s2
	ds_read_b32 v2, v0
	s_cbranch_vccnz .LBB0_490
	v_readlane_b32 s4, v252, 17
	v_readlane_b32 s5, v252, 18
	s_load_dwordx2 s[2:3], s[4:5], 0x4
	s_mov_b32 s9, 1
	s_waitcnt lgkmcnt(0)
	s_mul_i32 s8, s2, s29
	s_mul_i32 s8, s8, s3
	s_branch .LBB0_478

; DI void hgrn3_phase(bf16* Z2, const unsigned long long* OI, const float* gain, int gw, int NGW, int lane) {
;     const int fr = lane & 15, fq = lane >> 4;
;     for (int it = gw; it < 2048 * 4; it += NGW) {
;         const int unit = it >> 2, tt = it & 3, c = unit & 63, h = (unit >> 6) & 7, b = unit >> 9;
;         bf16* gp = Z2 + (size_t)(b * T + 64 * c + 16 * tt + fr) * NH2 + 3072 + h * 128 + 4 * fq;
.LBB0_761:
	v_readlane_b32 s100, v252, 0
	s_nop 3
	s_bfe_u32 s100, s100, 0x10003
	v_writelane_b32 v255, s100, 63
.Lswap8_first:
	s_or_b64 exec, exec, s[0:1]
	s_mov_b64 s[4:5], 0
	v_mov_b32_e32 v0, v238
	s_waitcnt lgkmcnt(0)
	s_barrier
	v_readlane_b32 s9, v252, 0
	v_readfirstlane_b32 s0, v0
	s_mov_b32 s10, s29
	s_ashr_i32 s3, s0, 6
	s_nop 1
	s_and_b32 s12, s9, 7
	s_lshr_b32 s13, s9, 3
	s_lshl_b32 s13, s13, 3
	s_add_u32 s13, s13, s3
	s_lshr_b32 s14, s12, 1
	s_lshl_b32 s14, s14, 11
	s_add_u32 s100, s14, 0x7ff
	s_and_b32 s12, s12, 1
	s_lshl_b32 s12, s12, 7
	s_add_u32 s14, s14, s12
	s_and_b32 s12, s13, 127
	s_add_u32 s14, s14, s12
	s_lshr_b32 s12, s13, 7
	s_lshl_b32 s12, s12, 8
	s_add_u32 s14, s14, s12
	s_lshr_b32 s9, s14, 3
	s_and_b32 s3, s14, 7
	s_movk_i32 s10, 64
	s_lshl_b32 s11, s9, 3
	s_add_i32 s6, s11, s3
	s_cmp_gt_i32 s6, s100
	v_xor_b32_e32 v246, 16, v239
	v_and_b32_e32 v247, 64, v239
	v_xor_b32_e32 v245, 32, v239
	s_cbranch_scc1 .LBB0_765
	v_readlane_b32 s14, v255, 63
	s_nop 3
	s_cmp_eq_u32 s14, 1
	s_cbranch_scc1 .LBB0_765
	v_and_b32_e32 v18, 15, v0
	v_and_b32_e32 v3, 63, v0
	v_lshrrev_b32_e32 v0, 2, v0
	s_add_u32 s0, s78, s4
	v_readlane_b32 s7, v254, 28
	v_and_b32_e32 v2, 12, v0
	v_add_u32_e32 v0, 64, v247
	s_addc_u32 s1, s79, s5
	s_lshl_b32 s86, s7, 10
	v_readlane_b32 s16, v252, 19
	v_cmp_lt_i32_e32 vcc, v246, v0
	s_lshl_b32 s2, s10, 3
	s_lshl_b64 s[12:13], s[86:87], 2
	v_readlane_b32 s18, v252, 21
	v_cndmask_b32_e32 v4, v239, v246, vcc
	v_cmp_lt_i32_e32 vcc, v245, v0
	v_readlane_b32 s19, v252, 22
	s_add_u32 s12, s18, s12
	v_cndmask_b32_e32 v0, v239, v245, vcc
	s_addc_u32 s13, s19, s13
	v_lshlrev_b32_e32 v20, 2, v0
	v_lshlrev_b32_e32 v0, 2, v2
	v_lshl_add_u64 v[6:7], s[12:13], 0, v[0:1]
	s_lshl_b32 s7, s9, 4
	s_lshl_b32 s8, s3, 1
	s_lshl_b32 s9, s9, 7
	s_lshl_b32 s12, s3, 4
	s_add_i32 s7, s7, s8
	s_lshl_b32 s8, s10, 4
	s_add_i32 s9, s9, s12
	s_lshl_b32 s10, s10, 7
	s_ashr_i32 s13, s3, 31
	s_ashr_i32 s14, s11, 31
	s_add_u32 s12, s3, s11
	s_addc_u32 s13, s13, s14
	s_lshl_b64 s[12:13], s[12:13], 12
	s_add_u32 s3, s4, s12
	s_addc_u32 s5, s5, s13
	v_readlane_b32 s4, v254, 23
	s_add_u32 s4, s4, s3
	v_readlane_b32 s3, v254, 24
	v_lshlrev_b32_e32 v0, 3, v3
	s_addc_u32 s5, s3, s5
	s_ashr_i32 s3, s2, 31
	v_lshlrev_b32_e32 v19, 2, v4
	v_lshl_add_u64 v[8:9], s[4:5], 0, v[0:1]
	s_lshl_b64 s[4:5], s[2:3], 12
	v_lshlrev_b32_e32 v0, 1, v2
	v_readlane_b32 s17, v252, 20
	v_readlane_b32 s20, v252, 23
	v_readlane_b32 s21, v252, 24
	v_readlane_b32 s22, v252, 25
	v_readlane_b32 s23, v252, 26
	v_readlane_b32 s24, v252, 27
	v_readlane_b32 s25, v252, 28
	v_readlane_b32 s26, v252, 29
	v_readlane_b32 s27, v252, 30
	v_readlane_b32 s28, v252, 31
	v_readlane_b32 s29, v252, 32
	v_readlane_b32 s30, v252, 33
	v_readlane_b32 s31, v252, 34

; #define REP(n) for (int rep_ = 0; rep_ < 1 + (n); ++rep_)
;     __host__ __device__ bool next(int i, Unit& u) const {
;         const long L = (long)i * G + c; if (L >= nwg) return false;
;         int wgid = (int)L; { const int q = nwg / NXCD, r = nwg % NXCD, xcd = wgid % NXCD, off = wgid / NXCD; wgid = (xcd < r ? xcd * (q + 1) : r * (q + 1) + (xcd - r) * q) + off; }
; __global__ void __launch_bounds__(512, 2) fwd_megakernel(Args a) {
;     ...
;         { FRESH(); hgrn3_phase(Z, (const unsigned long long*)(ws + WS_OG), (const float*)a.in[9] + (size_t)l * D, gw, NGW, lane); }
;         REP(PROBE_GEMM) { FRESH(); run_gemm(L, Xb, D, (const bf16*)(ws + W_IN) + (size_t)(NATT + NH2) * D, D, M, 2048, D, G, bid, EpiZ{Z, NH2, ssq}); }
.LBB0_765:
	v_readlane_b32 s100, v255, 63
	s_nop 3
	s_cmp_eq_u32 s100, 2
	s_cbranch_scc1 .LBB0_789
	s_mov_b64 s[0:1], 0
	v_mov_b32_e32 v0, v238
	s_mov_b32 s22, s29
	v_readlane_b32 s23, v252, 0
	v_mov_b32_e32 v16, v238
	s_cmpk_gt_i32 s23, 0x1ff
	v_readfirstlane_b32 s4, v16
	s_cbranch_scc1 .LBB0_789
	s_ashr_i32 s24, s23, 31
	s_lshr_b32 s2, s24, 29
	s_add_i32 s6, s23, s2
	s_and_b32 s2, s6, -8
	s_sub_i32 s5, s23, s2
	s_cmp_gt_i32 s5, -1
	s_mov_b64 s[2:3], -1
	s_cbranch_scc0 .LBB0_768
	s_lshl_b32 s9, s5, 6
	s_mov_b64 s[2:3], 0

; #define PG8_WAIT_V(n) asm volatile("s_waitcnt vmcnt(" #n ")" ::: "memory")
; #define PG8_BAR __builtin_amdgcn_s_barrier()
; template <class Epi, class Sched, bool ALIGN_EPI = false, bool SP2 = false>
; __device__ __forceinline__ void gemm_phase(PG8_LAS unsigned char* lds, const Gemm g, const Sched& S, const Epi& E) {
;     ...
;     PG8_WAIT_V(0);
;     if constexpr (!ALIGN_EPI) { if (wr == 0) PG8_BAR; }
;     PG8_BAR;
.LBB0_788:
	s_waitcnt vmcnt(0)
	v_readlane_b32 s30, v254, 31
	v_readlane_b32 s26, v254, 33
	v_readlane_b32 s29, v252, 39
	v_readlane_b32 s31, v254, 32
	v_readlane_b32 s27, v254, 34
	s_barrier
	v_readlane_b32 s100, v255, 63
	s_nop 3
	s_cmp_eq_u32 s100, 1
	s_cbranch_scc0 .Lswap8_done
	s_mov_b32 s100, 2
	v_writelane_b32 v255, s100, 63
	s_branch .Lswap8_first
